# grid barrier: completing workgroup publishes the generation to every XCD word directly; XCD leaders stop republishing/waiting
# speedup vs baseline: 1.0028x; 1.0028x over previous
; DI unsigned xb_ld(unsigned* p)              { return __hip_atomic_load(p, __ATOMIC_RELAXED, __HIP_MEMORY_SCOPE_AGENT); }
; DI unsigned xb_add(unsigned* p, unsigned v) { return __hip_atomic_fetch_add(p, v, __ATOMIC_RELAXED, __HIP_MEMORY_SCOPE_AGENT); }
; #define XB_SPIN(cond, bar) do { unsigned _sp = 0; while (cond) { __builtin_amdgcn_s_sleep(1); \
;     if ((++_sp & 255u) == 0u) { if (xb_ld(&(bar)[XB_TMO])) break; if (_sp > XB_SPIN_CAP) { atomicAdd(&(bar)[XB_TMO], 1u); break; } } } } while (0)
; DI void xcd_barrier(const XcdBarrier& b) {
;     ...
;     const unsigned old = xb_add(&bar[XB_XSUB(bx)], 1u);
;     const unsigned gen = old / nloc;
;     if (old + 1u == (gen + 1u) * nloc) {
;       __builtin_amdgcn_fence(__ATOMIC_RELEASE, "agent");
;       asm volatile("s_waitcnt vmcnt(0)" ::: "memory");
;       const unsigned og = xb_add(&bar[XB_TOP], 1u);
;       const unsigned tg = og / nx;
;       if (og + 1u == (tg + 1u) * nx) xb_add(&bar[XB_TOPGEN], 1u);
;       else XB_SPIN(xb_ld(&bar[XB_TOPGEN]) == tg, bar);
.LBB0_204:
	s_or_b64 exec, exec, s[4:5]
	v_cvt_f32_u32_e32 v2, v5
	s_waitcnt vmcnt(0)
	v_readfirstlane_b32 s2, v1
	s_add_u32 s4, s54, 0x329dbb00
	s_addc_u32 s5, s55, 0
	v_rcp_iflag_f32_e32 v2, v2
	v_add_u32_e32 v0, s2, v0
	v_add_u32_e32 v3, 1, v0
	s_mov_b64 s[6:7], -1
	v_mul_f32_e32 v1, 0x4f7ffffe, v2
	v_cvt_u32_f32_e32 v1, v1
	v_sub_u32_e32 v2, 0, v5
	v_mul_lo_u32 v2, v2, v1
	v_mul_hi_u32 v2, v1, v2
	v_add_u32_e32 v1, v1, v2
	v_mul_hi_u32 v1, v0, v1
	v_mul_lo_u32 v2, v1, v5
	v_sub_u32_e32 v0, v0, v2
	v_add_u32_e32 v6, 1, v1
	v_cmp_ge_u32_e32 vcc, v0, v5
	v_sub_u32_e32 v2, v0, v5
	s_nop 0
	v_cndmask_b32_e32 v1, v1, v6, vcc
	v_cndmask_b32_e32 v0, v0, v2, vcc
	v_add_u32_e32 v2, 1, v1
	v_cmp_ge_u32_e32 vcc, v0, v5
	s_nop 1
	v_cndmask_b32_e32 v2, v1, v2, vcc
	v_mul_lo_u32 v0, v5, v2
	v_add_u32_e32 v0, v0, v5
	v_cmp_ne_u32_e32 vcc, v3, v0
	v_mov_b64_e32 v[0:1], s[4:5]
	s_mov_b32 s101, vcc_lo
	s_and_saveexec_b64 s[2:3], vcc
	s_cbranch_execz .LBB0_216
	v_mov_b32_e32 v0, 0
	global_load_dword v1, v0, s[4:5] sc1
	s_mov_b64 s[10:11], 0
	s_waitcnt vmcnt(0)
	v_cmp_eq_u32_e32 vcc, v1, v2
	s_and_saveexec_b64 s[8:9], vcc
	s_cbranch_execz .LBB0_215
	s_add_u32 s6, s54, 0x329d8800
	s_addc_u32 s7, s55, 0
	s_mov_b32 s20, 1
	s_branch .LBB0_208

; DI unsigned xb_ld(unsigned* p)              { return __hip_atomic_load(p, __ATOMIC_RELAXED, __HIP_MEMORY_SCOPE_AGENT); }
; DI unsigned xb_add(unsigned* p, unsigned v) { return __hip_atomic_fetch_add(p, v, __ATOMIC_RELAXED, __HIP_MEMORY_SCOPE_AGENT); }
; #define XB_SPIN(cond, bar) do { unsigned _sp = 0; while (cond) { __builtin_amdgcn_s_sleep(1); \
;     if ((++_sp & 255u) == 0u) { if (xb_ld(&(bar)[XB_TMO])) break; if (_sp > XB_SPIN_CAP) { atomicAdd(&(bar)[XB_TMO], 1u); break; } } } } while (0)
; DI void xcd_barrier(const XcdBarrier& b) {
;     ...
;       if (og + 1u == (tg + 1u) * nx) xb_add(&bar[XB_TOPGEN], 1u);
;       else XB_SPIN(xb_ld(&bar[XB_TOPGEN]) == tg, bar);
;       __builtin_amdgcn_fence(__ATOMIC_ACQUIRE, "agent");
;       xb_add(&bar[XB_XGEN(bx)], 1u);
;       asm volatile("s_waitcnt vmcnt(0)" ::: "memory");
.LBB0_216:
	s_or_b64 exec, exec, s[2:3]
	s_and_saveexec_b64 s[2:3], s[6:7]
	s_cbranch_execz .LBB0_218
	v_mov_b32_e32 v2, 1
	global_atomic_add v[0:1], v2, off
	s_cmp_lg_u32 s101, 0
	s_cbranch_scc1 .Lxg0_skip
	v_subrev_co_u32_e32 v0, vcc, 0x1100, v0
	s_nop 1
	v_subbrev_co_u32_e32 v1, vcc, 0, v1, vcc
	global_atomic_add v[0:1], v2, off
	global_atomic_add v[0:1], v2, off offset:256
	global_atomic_add v[0:1], v2, off offset:512
	global_atomic_add v[0:1], v2, off offset:768
	global_atomic_add v[0:1], v2, off offset:1024
	global_atomic_add v[0:1], v2, off offset:1280
	global_atomic_add v[0:1], v2, off offset:1536
	global_atomic_add v[0:1], v2, off offset:1792
.Lxg0_skip:
.LBB0_218:
	s_or_b64 exec, exec, s[2:3]
	v_readlane_b32 s2, v249, 48
	v_add_u32_e32 v0, 0x900, v4
	v_mov_b32_e32 v1, 0
	v_readlane_b32 s3, v249, 49
	v_mov_b32_e32 v2, 1
	v_lshl_add_u64 v[0:1], v[0:1], 2, s[2:3]

; DI unsigned xb_ld(unsigned* p)              { return __hip_atomic_load(p, __ATOMIC_RELAXED, __HIP_MEMORY_SCOPE_AGENT); }
; DI unsigned xb_add(unsigned* p, unsigned v) { return __hip_atomic_fetch_add(p, v, __ATOMIC_RELAXED, __HIP_MEMORY_SCOPE_AGENT); }
; #define XB_SPIN(cond, bar) do { unsigned _sp = 0; while (cond) { __builtin_amdgcn_s_sleep(1); \
;     if ((++_sp & 255u) == 0u) { if (xb_ld(&(bar)[XB_TMO])) break; if (_sp > XB_SPIN_CAP) { atomicAdd(&(bar)[XB_TMO], 1u); break; } } } } while (0)
; DI void xcd_barrier(const XcdBarrier& b) {
;     ...
;     const unsigned old = xb_add(&bar[XB_XSUB(bx)], 1u);
;     const unsigned gen = old / nloc;
;     if (old + 1u == (gen + 1u) * nloc) {
;       __builtin_amdgcn_fence(__ATOMIC_RELEASE, "agent");
;       asm volatile("s_waitcnt vmcnt(0)" ::: "memory");
;       const unsigned og = xb_add(&bar[XB_TOP], 1u);
;       const unsigned tg = og / nx;
;       if (og + 1u == (tg + 1u) * nx) xb_add(&bar[XB_TOPGEN], 1u);
;       else XB_SPIN(xb_ld(&bar[XB_TOPGEN]) == tg, bar);
.LBB0_721:
	s_or_b64 exec, exec, s[4:5]
	s_waitcnt vmcnt(0)
	v_readfirstlane_b32 s2, v4
	v_cvt_f32_u32_e32 v4, v3
	v_sub_u32_e32 v5, 0, v3
	v_add_u32_e32 v2, s2, v2
	v_readlane_b32 s2, v250, 50
	v_rcp_iflag_f32_e32 v4, v4
	v_readlane_b32 s3, v250, 51
	s_mov_b64 s[4:5], -1
	v_mul_f32_e32 v4, 0x4f7ffffe, v4
	v_cvt_u32_f32_e32 v4, v4
	v_mul_lo_u32 v5, v5, v4
	v_mul_hi_u32 v5, v4, v5
	v_add_u32_e32 v4, v4, v5
	v_mul_hi_u32 v4, v2, v4
	v_mul_lo_u32 v5, v4, v3
	v_sub_u32_e32 v5, v2, v5
	v_cmp_ge_u32_e32 vcc, v5, v3
	v_add_u32_e32 v6, 1, v4
	v_add_u32_e32 v2, 1, v2
	v_cndmask_b32_e32 v4, v4, v6, vcc
	v_sub_u32_e32 v6, v5, v3
	v_cndmask_b32_e32 v5, v5, v6, vcc
	v_cmp_ge_u32_e32 vcc, v5, v3
	v_add_u32_e32 v5, 1, v4
	s_nop 0
	v_cndmask_b32_e32 v4, v4, v5, vcc
	v_mul_lo_u32 v5, v3, v4
	v_add_u32_e32 v3, v5, v3
	v_cmp_ne_u32_e32 vcc, v2, v3
	v_mov_b64_e32 v[2:3], s[2:3]
	s_mov_b32 s101, vcc_lo
	s_and_saveexec_b64 s[2:3], vcc
	s_cbranch_execz .LBB0_733
	v_readlane_b32 s4, v250, 50
	v_readlane_b32 s5, v250, 51
	s_mov_b64 s[6:7], 0
	s_nop 3
	global_load_dword v2, v1, s[4:5] sc1
	s_waitcnt vmcnt(0)
	v_cmp_eq_u32_e32 vcc, v2, v4
	s_and_saveexec_b64 s[4:5], vcc
	s_cbranch_execz .LBB0_732
	s_mov_b32 s16, 1
	s_branch .LBB0_725

; DI unsigned xb_ld(unsigned* p)              { return __hip_atomic_load(p, __ATOMIC_RELAXED, __HIP_MEMORY_SCOPE_AGENT); }
; DI unsigned xb_add(unsigned* p, unsigned v) { return __hip_atomic_fetch_add(p, v, __ATOMIC_RELAXED, __HIP_MEMORY_SCOPE_AGENT); }
; #define XB_SPIN(cond, bar) do { unsigned _sp = 0; while (cond) { __builtin_amdgcn_s_sleep(1); \
;     if ((++_sp & 255u) == 0u) { if (xb_ld(&(bar)[XB_TMO])) break; if (_sp > XB_SPIN_CAP) { atomicAdd(&(bar)[XB_TMO], 1u); break; } } } } while (0)
; DI void xcd_barrier(const XcdBarrier& b) {
;     ...
;       if (og + 1u == (tg + 1u) * nx) xb_add(&bar[XB_TOPGEN], 1u);
;       else XB_SPIN(xb_ld(&bar[XB_TOPGEN]) == tg, bar);
;       __builtin_amdgcn_fence(__ATOMIC_ACQUIRE, "agent");
;       xb_add(&bar[XB_XGEN(bx)], 1u);
;       asm volatile("s_waitcnt vmcnt(0)" ::: "memory");
.LBB0_733:
	s_or_b64 exec, exec, s[2:3]
	s_and_saveexec_b64 s[2:3], s[4:5]
	s_cbranch_execz .LBB0_735
	v_mov_b32_e32 v4, 1
	global_atomic_add v[2:3], v4, off
	s_cmp_lg_u32 s101, 0
	s_cbranch_scc1 .Lxg2_skip
	v_subrev_co_u32_e32 v2, vcc, 0x1100, v2
	s_nop 1
	v_subbrev_co_u32_e32 v3, vcc, 0, v3, vcc
	global_atomic_add v[2:3], v4, off
	global_atomic_add v[2:3], v4, off offset:256
	global_atomic_add v[2:3], v4, off offset:512
	global_atomic_add v[2:3], v4, off offset:768
	global_atomic_add v[2:3], v4, off offset:1024
	global_atomic_add v[2:3], v4, off offset:1280
	global_atomic_add v[2:3], v4, off offset:1536
	global_atomic_add v[2:3], v4, off offset:1792
.Lxg2_skip:
.LBB0_735:
	s_or_b64 exec, exec, s[2:3]
	v_readlane_b32 s2, v249, 48
	v_readlane_b32 s3, v249, 49
	v_lshl_add_u64 v[2:3], v[0:1], 2, s[2:3]
	v_mov_b32_e32 v0, 1

; DI unsigned xb_ld(unsigned* p)              { return __hip_atomic_load(p, __ATOMIC_RELAXED, __HIP_MEMORY_SCOPE_AGENT); }
; DI unsigned xb_add(unsigned* p, unsigned v) { return __hip_atomic_fetch_add(p, v, __ATOMIC_RELAXED, __HIP_MEMORY_SCOPE_AGENT); }
; #define XB_SPIN(cond, bar) do { unsigned _sp = 0; while (cond) { __builtin_amdgcn_s_sleep(1); \
;     if ((++_sp & 255u) == 0u) { if (xb_ld(&(bar)[XB_TMO])) break; if (_sp > XB_SPIN_CAP) { atomicAdd(&(bar)[XB_TMO], 1u); break; } } } } while (0)
; DI void xcd_barrier(const XcdBarrier& b) {
;     ...
;     const unsigned old = xb_add(&bar[XB_XSUB(bx)], 1u);
;     const unsigned gen = old / nloc;
;     if (old + 1u == (gen + 1u) * nloc) {
;       __builtin_amdgcn_fence(__ATOMIC_RELEASE, "agent");
;       asm volatile("s_waitcnt vmcnt(0)" ::: "memory");
;       const unsigned og = xb_add(&bar[XB_TOP], 1u);
;       const unsigned tg = og / nx;
;       if (og + 1u == (tg + 1u) * nx) xb_add(&bar[XB_TOPGEN], 1u);
;       else XB_SPIN(xb_ld(&bar[XB_TOPGEN]) == tg, bar);
.LBB0_1640:
	s_or_b64 exec, exec, s[4:5]
	s_waitcnt vmcnt(0)
	v_readfirstlane_b32 s2, v4
	v_cvt_f32_u32_e32 v4, v3
	v_sub_u32_e32 v5, 0, v3
	v_add_u32_e32 v2, s2, v2
	v_readlane_b32 s2, v250, 50
	v_rcp_iflag_f32_e32 v4, v4
	v_readlane_b32 s3, v250, 51
	s_mov_b64 s[4:5], -1
	v_mul_f32_e32 v4, 0x4f7ffffe, v4
	v_cvt_u32_f32_e32 v4, v4
	v_mul_lo_u32 v5, v5, v4
	v_mul_hi_u32 v5, v4, v5
	v_add_u32_e32 v4, v4, v5
	v_mul_hi_u32 v4, v2, v4
	v_mul_lo_u32 v5, v4, v3
	v_sub_u32_e32 v5, v2, v5
	v_cmp_ge_u32_e32 vcc, v5, v3
	v_add_u32_e32 v6, 1, v4
	v_add_u32_e32 v2, 1, v2
	v_cndmask_b32_e32 v4, v4, v6, vcc
	v_sub_u32_e32 v6, v5, v3
	v_cndmask_b32_e32 v5, v5, v6, vcc
	v_cmp_ge_u32_e32 vcc, v5, v3
	v_add_u32_e32 v5, 1, v4
	s_nop 0
	v_cndmask_b32_e32 v4, v4, v5, vcc
	v_mul_lo_u32 v5, v3, v4
	v_add_u32_e32 v3, v5, v3
	v_cmp_ne_u32_e32 vcc, v2, v3
	v_mov_b64_e32 v[2:3], s[2:3]
	s_mov_b32 s101, vcc_lo
	s_and_saveexec_b64 s[2:3], vcc
	s_cbranch_execz .LBB0_1652
	v_readlane_b32 s4, v250, 50
	v_readlane_b32 s5, v250, 51
	s_mov_b64 s[8:9], 0
	s_nop 3
	global_load_dword v2, v1, s[4:5] sc1
	s_waitcnt vmcnt(0)
	v_cmp_eq_u32_e32 vcc, v2, v4
	s_and_saveexec_b64 s[4:5], vcc
	s_cbranch_execz .LBB0_1651
	s_mov_b32 s18, 1
	s_branch .LBB0_1644
